# per-block gate scores: all eight k-mean fragment reads issued up front (dead registers v[24:47]) with counted waits instead of six serial read->MFMA round trips
# baseline (speedup 1.0000x reference)
; __device__ __forceinline__ unsigned gate_select(const bf16x8* qr, const char* lds, int qb, int r32, int hi) {
;     if (qb <= 3) return (1u << qb) - 1u;
;     f32x16 p = {};
;     const char* kp = lds + KM_LDS_OFF + r32 * KM_PITCH + hi * 16;
; #pragma unroll
;     for (int d0 = 0; d0 < 8; ++d0) {
;         const bf16x8 frag = *(const bf16x8*)(kp + d0 * 32);
;         p = __builtin_amdgcn_mfma_f32_32x32x16_bf16(frag, qr[d0], p, 0, 0, 0);
;     }
;     float g[16];
; #pragma unroll
;     for (int r = 0; r < 8; ++r) { const float v = p[r] + p[r + 8];
;         auto rr = __builtin_amdgcn_permlane32_swap(__float_as_uint(v), __float_as_uint(v), false, false);
;         g[(r & 3) + 8 * (r >> 2)] = __uint_as_float(rr[0]); g[(r & 3) + 8 * (r >> 2) + 4] = __uint_as_float(rr[1]); }
;     unsigned sel = 0u;
; #pragma unroll
;     for (int pass = 0; pass < 3; ++pass) { float best = -__builtin_inff(); int bi = -1;
; #pragma unroll
;         for (int n = 0; n < 16; ++n) { const bool ok = (n < qb) && !((sel >> n) & 1u) && (g[n] > best); best = ok ? g[n] : best; bi = ok ? n : bi; }
;         if (bi >= 0) sel |= 1u << bi; }
;     return sel;
.LBB0_82:
	v_mov_b32_e32 v183, v0
	s_cmp_gt_i32 s44, 3
	v_bfe_u32 v182, v183, 5, 1
	v_readfirstlane_b32 s3, v183
	v_and_b32_e32 v184, 31, v183
	v_lshlrev_b32_e32 v164, 4, v182
	s_mov_b64 s[0:1], -1
	s_cbranch_scc0 .LBB0_84
	v_mul_u32_u24_e32 v2, 0x110, v184
	v_readlane_b32 s0, v255, 35
	s_cmp_lg_u32 s44, 4
	s_cselect_b64 s[42:43], -1, 0
	v_add3_u32 v22, s0, v2, v164
	ds_read_b128 v[2:5], v22
	ds_read_b128 v[18:21], v22 offset:32
	ds_read_b128 v[24:27], v22 offset:64
	ds_read_b128 v[28:31], v22 offset:96
	ds_read_b128 v[32:35], v22 offset:128
	ds_read_b128 v[36:39], v22 offset:160
	ds_read_b128 v[40:43], v22 offset:192
	ds_read_b128 v[44:47], v22 offset:224
	s_mov_b32 s0, 0xff800000
	s_waitcnt lgkmcnt(7)
	v_mfma_f32_32x32x16_bf16 v[2:17], v[2:5], v[132:135], 0
	s_waitcnt lgkmcnt(6)
	v_mfma_f32_32x32x16_bf16 v[2:17], v[18:21], v[128:131], v[2:17]
	s_waitcnt lgkmcnt(5)
	v_mfma_f32_32x32x16_bf16 v[2:17], v[24:27], v[124:127], v[2:17]
	s_waitcnt lgkmcnt(4)
	v_mfma_f32_32x32x16_bf16 v[2:17], v[28:31], v[120:123], v[2:17]
	s_waitcnt lgkmcnt(3)
	v_mfma_f32_32x32x16_bf16 v[2:17], v[32:35], v[116:119], v[2:17]
	s_waitcnt lgkmcnt(2)
	v_mfma_f32_32x32x16_bf16 v[2:17], v[36:39], v[112:115], v[2:17]
	s_waitcnt lgkmcnt(1)
	v_mfma_f32_32x32x16_bf16 v[2:17], v[40:43], v[108:111], v[2:17]
	s_waitcnt lgkmcnt(0)
	v_mfma_f32_32x32x16_bf16 v[2:17], v[44:47], v[104:107], v[2:17]
	s_nop 11
	v_add_f32_e32 v2, v2, v10
	v_mov_b32_e32 v10, v2
	v_add_f32_e32 v3, v3, v11
	s_nop 0
	v_permlane32_swap_b32_e32 v2, v10
	v_add_f32_e32 v9, v9, v17
	v_mov_b32_e32 v11, v3
	v_cmp_nlg_f32_e32 vcc, s0, v2
	v_add_f32_e32 v4, v4, v12
	v_mov_b32_e32 v17, v9
	v_permlane32_swap_b32_e32 v3, v11
	v_cndmask_b32_e32 v18, v2, v220, vcc
	v_mov_b32_e32 v12, v4
	v_permlane32_swap_b32_e32 v9, v17
	v_cmp_lt_f32_e64 s[38:39], v18, v3
	v_add_f32_e32 v5, v5, v13
	v_permlane32_swap_b32_e32 v4, v12
	v_cndmask_b32_e64 v17, 0, -1, vcc
	v_cndmask_b32_e64 v18, v18, v3, s[38:39]
	v_mov_b32_e32 v13, v5
	v_cndmask_b32_e64 v17, v17, 1, s[38:39]
	v_cmp_lt_f32_e64 s[38:39], v18, v4
	v_permlane32_swap_b32_e32 v5, v13
	s_nop 0
	v_cndmask_b32_e64 v18, v18, v4, s[38:39]
	v_cndmask_b32_e64 v17, v17, 2, s[38:39]
	v_cmp_lt_f32_e64 s[38:39], v18, v5
	v_add_f32_e32 v6, v6, v14
	v_mov_b32_e32 v14, v6
	v_cndmask_b32_e64 v18, v18, v5, s[38:39]
	v_cndmask_b32_e64 v17, v17, 3, s[38:39]
	v_cmp_lt_f32_e64 s[38:39], v18, v10
	s_and_b64 s[38:39], s[42:43], s[38:39]
	s_cmp_gt_u32 s44, 5
	v_cndmask_b32_e64 v18, v18, v10, s[38:39]
	v_cndmask_b32_e64 v17, v17, 4, s[38:39]
	s_cselect_b64 s[24:25], -1, 0
	v_cmp_lt_f32_e64 s[38:39], v18, v11
	s_and_b64 s[38:39], s[24:25], s[38:39]
	s_cmp_gt_u32 s44, 6
	v_cndmask_b32_e64 v18, v18, v11, s[38:39]
	v_cndmask_b32_e64 v17, v17, 5, s[38:39]
	s_cselect_b64 s[80:81], -1, 0
	v_cmp_lt_f32_e64 s[38:39], v18, v12
	s_and_b64 s[38:39], s[80:81], s[38:39]
	s_cmp_gt_u32 s44, 7
	v_cndmask_b32_e64 v18, v18, v12, s[38:39]
	v_cndmask_b32_e64 v17, v17, 6, s[38:39]
	s_cselect_b64 s[6:7], -1, 0
	v_cmp_lt_f32_e64 s[38:39], v18, v13
	s_and_b64 s[38:39], s[6:7], s[38:39]
	v_permlane32_swap_b32_e32 v6, v14
	v_cndmask_b32_e64 v18, v18, v13, s[38:39]
	s_cmp_gt_u32 s44, 8
	v_add_f32_e32 v7, v7, v15
	v_cndmask_b32_e64 v17, v17, 7, s[38:39]
	s_cselect_b64 s[26:27], -1, 0
	v_cmp_lt_f32_e64 s[38:39], v18, v6
	v_mov_b32_e32 v15, v7
	s_and_b64 s[38:39], s[26:27], s[38:39]
	s_nop 0
	v_permlane32_swap_b32_e32 v7, v15
	v_cndmask_b32_e64 v18, v18, v6, s[38:39]
	s_cmp_gt_u32 s44, 9
	v_add_f32_e32 v8, v8, v16
	v_cndmask_b32_e64 v17, v17, 8, s[38:39]
	s_cselect_b64 s[0:1], -1, 0
	v_cmp_lt_f32_e64 s[38:39], v18, v7
	v_mov_b32_e32 v16, v8
	s_and_b64 s[38:39], s[0:1], s[38:39]
	s_nop 0
	v_permlane32_swap_b32_e32 v8, v16
	v_cndmask_b32_e64 v18, v18, v7, s[38:39]
	s_cmp_gt_u32 s44, 10
	v_cndmask_b32_e64 v17, v17, 9, s[38:39]
	s_cselect_b64 s[98:99], -1, 0
	v_cmp_lt_f32_e64 s[38:39], v18, v8
	s_and_b64 s[38:39], s[98:99], s[38:39]
	s_cmp_gt_u32 s44, 11
	v_cndmask_b32_e64 v18, v18, v8, s[38:39]
	v_cndmask_b32_e64 v17, v17, 10, s[38:39]
	s_cselect_b64 s[96:97], -1, 0
	v_cmp_lt_f32_e64 s[38:39], v18, v9
	s_and_b64 s[38:39], s[96:97], s[38:39]
	s_cmp_gt_u32 s44, 12
	v_cndmask_b32_e64 v18, v18, v9, s[38:39]
	v_cndmask_b32_e64 v17, v17, 11, s[38:39]
	s_cselect_b64 s[94:95], -1, 0
	v_cmp_lt_f32_e64 s[38:39], v18, v14
	s_and_b64 s[38:39], s[94:95], s[38:39]
	s_cmp_gt_u32 s44, 13
	v_cndmask_b32_e64 v18, v18, v14, s[38:39]
	v_cndmask_b32_e64 v17, v17, 12, s[38:39]
	s_cselect_b64 s[90:91], -1, 0
	v_cmp_lt_f32_e64 s[38:39], v18, v15
	s_and_b64 s[38:39], s[90:91], s[38:39]
	s_cmp_gt_u32 s44, 14
	v_cndmask_b32_e64 v18, v18, v15, s[38:39]
	v_cndmask_b32_e64 v17, v17, 13, s[38:39]
	s_cselect_b64 s[12:13], -1, 0
	v_cmp_lt_f32_e64 s[38:39], v18, v16
	s_and_b64 s[8:9], s[12:13], s[38:39]
	v_cndmask_b32_e64 v17, v17, 14, s[8:9]
	v_lshlrev_b32_e64 v18, v17, 1
	v_cmp_lt_i32_e64 s[38:39], -1, v17
	s_nop 1
	v_cndmask_b32_e64 v17, 0, v18, s[38:39]
	v_and_b32_e32 v18, 1, v17
	v_cmp_eq_u32_e64 s[38:39], 1, v18
	s_or_b64 s[38:39], s[38:39], vcc
	v_and_b32_e32 v20, 2, v17
	v_cndmask_b32_e64 v19, v2, v220, s[38:39]
	v_cndmask_b32_e64 v18, 0, -1, s[38:39]
	v_cmp_eq_u32_e64 s[38:39], 0, v20
	v_cmp_lt_f32_e64 s[40:41], v19, v3
	s_and_b64 s[38:39], s[38:39], s[40:41]
	v_cndmask_b32_e64 v19, v19, v3, s[38:39]
	v_and_b32_e32 v20, 4, v17
	v_cndmask_b32_e64 v18, v18, 1, s[38:39]
	v_cmp_eq_u32_e64 s[38:39], 0, v20
	v_cmp_lt_f32_e64 s[40:41], v19, v4
	s_and_b64 s[38:39], s[38:39], s[40:41]
	v_cndmask_b32_e64 v19, v19, v4, s[38:39]
	v_and_b32_e32 v20, 8, v17
	v_cndmask_b32_e64 v18, v18, 2, s[38:39]
	v_cmp_eq_u32_e64 s[38:39], 0, v20
	v_cmp_lt_f32_e64 s[40:41], v19, v5
; __device__ __forceinline__ unsigned gate_select(const bf16x8* qr, const char* lds, int qb, int r32, int hi) {
;     ...
;     unsigned sel = 0u;
; #pragma unroll
;     for (int pass = 0; pass < 3; ++pass) { float best = -__builtin_inff(); int bi = -1;
; #pragma unroll
;         for (int n = 0; n < 16; ++n) { const bool ok = (n < qb) && !((sel >> n) & 1u) && (g[n] > best); best = ok ? g[n] : best; bi = ok ? n : bi; }
;         if (bi >= 0) sel |= 1u << bi; }
;     return sel;
	s_and_b64 s[38:39], s[38:39], s[40:41]
	v_and_b32_e32 v20, 16, v17
	v_cndmask_b32_e64 v18, v18, 3, s[38:39]
	v_cndmask_b32_e64 v19, v19, v5, s[38:39]
	v_cmp_eq_u32_e64 s[38:39], 0, v20
	s_and_b64 s[8:9], s[42:43], s[38:39]
	v_cmp_lt_f32_e64 s[38:39], v19, v10
	s_and_b64 s[38:39], s[8:9], s[38:39]
	v_and_b32_e32 v20, 32, v17
	v_cndmask_b32_e64 v18, v18, 4, s[38:39]
	v_cndmask_b32_e64 v19, v19, v10, s[38:39]
	v_cmp_eq_u32_e64 s[38:39], 0, v20
	s_and_b64 s[8:9], s[24:25], s[38:39]
	v_cmp_lt_f32_e64 s[38:39], v19, v11
	s_and_b64 s[38:39], s[8:9], s[38:39]
	v_and_b32_e32 v20, 64, v17
	v_cndmask_b32_e64 v18, v18, 5, s[38:39]
	v_cndmask_b32_e64 v19, v19, v11, s[38:39]
	v_cmp_eq_u32_e64 s[38:39], 0, v20
	s_and_b64 s[8:9], s[80:81], s[38:39]
	v_cmp_lt_f32_e64 s[38:39], v19, v12
	s_and_b64 s[38:39], s[8:9], s[38:39]
	v_and_b32_e32 v20, 0x80, v17
	v_cndmask_b32_e64 v18, v18, 6, s[38:39]
	v_cndmask_b32_e64 v19, v19, v12, s[38:39]
	v_cmp_eq_u32_e64 s[38:39], 0, v20
	s_and_b64 s[8:9], s[6:7], s[38:39]
	v_cmp_lt_f32_e64 s[38:39], v19, v13
	s_and_b64 s[38:39], s[8:9], s[38:39]
	v_and_b32_e32 v20, 0x100, v17
	v_cndmask_b32_e64 v18, v18, 7, s[38:39]
	v_cndmask_b32_e64 v19, v19, v13, s[38:39]
	v_cmp_eq_u32_e64 s[38:39], 0, v20
	s_and_b64 s[8:9], s[26:27], s[38:39]
	v_cmp_lt_f32_e64 s[38:39], v19, v6
	s_and_b64 s[38:39], s[8:9], s[38:39]
	v_and_b32_e32 v20, 0x200, v17
	v_cndmask_b32_e64 v18, v18, 8, s[38:39]
	v_cndmask_b32_e64 v19, v19, v6, s[38:39]
	v_cmp_eq_u32_e64 s[38:39], 0, v20
	s_and_b64 s[8:9], s[0:1], s[38:39]
	v_cmp_lt_f32_e64 s[38:39], v19, v7
	s_and_b64 s[38:39], s[8:9], s[38:39]
	v_and_b32_e32 v20, 0x400, v17
	v_cndmask_b32_e64 v18, v18, 9, s[38:39]
	v_cndmask_b32_e64 v19, v19, v7, s[38:39]
	v_cmp_eq_u32_e64 s[38:39], 0, v20
	s_and_b64 s[8:9], s[98:99], s[38:39]
	v_cmp_lt_f32_e64 s[38:39], v19, v8
	s_and_b64 s[38:39], s[8:9], s[38:39]
	v_and_b32_e32 v20, 0x800, v17
	v_cndmask_b32_e64 v18, v18, 10, s[38:39]
	v_cndmask_b32_e64 v19, v19, v8, s[38:39]
	v_cmp_eq_u32_e64 s[38:39], 0, v20
	s_and_b64 s[8:9], s[96:97], s[38:39]
	v_cmp_lt_f32_e64 s[38:39], v19, v9
	s_and_b64 s[38:39], s[8:9], s[38:39]
	v_and_b32_e32 v20, 0x1000, v17
	v_cndmask_b32_e64 v18, v18, 11, s[38:39]
	v_cndmask_b32_e64 v19, v19, v9, s[38:39]
	v_cmp_eq_u32_e64 s[38:39], 0, v20
	s_and_b64 s[8:9], s[94:95], s[38:39]
	v_cmp_lt_f32_e64 s[38:39], v19, v14
	s_and_b64 s[38:39], s[8:9], s[38:39]
	v_and_b32_e32 v20, 0x2000, v17
	v_cndmask_b32_e64 v18, v18, 12, s[38:39]
	v_cndmask_b32_e64 v19, v19, v14, s[38:39]
	v_cmp_eq_u32_e64 s[38:39], 0, v20
	s_and_b64 s[8:9], s[90:91], s[38:39]
	v_cmp_lt_f32_e64 s[38:39], v19, v15
	s_and_b64 s[38:39], s[8:9], s[38:39]
	v_and_b32_e32 v20, 0x4000, v17
	v_cndmask_b32_e64 v18, v18, 13, s[38:39]
	v_cndmask_b32_e64 v19, v19, v15, s[38:39]
	v_cmp_eq_u32_e64 s[38:39], 0, v20
	s_and_b64 s[8:9], s[12:13], s[38:39]
	v_cmp_lt_f32_e64 s[38:39], v19, v16
	s_and_b64 s[8:9], s[8:9], s[38:39]
	v_cndmask_b32_e64 v18, v18, 14, s[8:9]
	v_lshlrev_b32_e64 v19, v18, 1
	v_cmp_lt_i32_e64 s[38:39], -1, v18
	s_nop 1
	v_cndmask_b32_e64 v18, 0, v19, s[38:39]
	v_or_b32_e32 v19, v18, v17
	v_and_b32_e32 v20, 1, v19
	v_cmp_eq_u32_e64 s[38:39], 1, v20
	s_or_b64 vcc, s[38:39], vcc
	v_cndmask_b32_e32 v2, v2, v220, vcc
	v_bitop3_b32 v21, v18, 2, v17 bitop3:0xc8
	v_cndmask_b32_e64 v20, 0, -1, vcc
	v_cmp_eq_u32_e32 vcc, 0, v21
	v_cmp_lt_f32_e64 s[38:39], v2, v3
	s_and_b64 vcc, vcc, s[38:39]
	v_cndmask_b32_e32 v2, v2, v3, vcc
	v_bitop3_b32 v3, v18, 4, v17 bitop3:0xc8
	v_cndmask_b32_e64 v20, v20, 1, vcc
	v_cmp_eq_u32_e32 vcc, 0, v3
	v_cmp_lt_f32_e64 s[38:39], v2, v4
	s_and_b64 vcc, vcc, s[38:39]
	v_cndmask_b32_e32 v2, v2, v4, vcc
	v_bitop3_b32 v4, v18, 8, v17 bitop3:0xc8
	v_cndmask_b32_e64 v3, v20, 2, vcc
	v_cmp_eq_u32_e32 vcc, 0, v4
	v_cmp_lt_f32_e64 s[38:39], v2, v5
	s_and_b64 vcc, vcc, s[38:39]
	v_bitop3_b32 v4, v18, 16, v17 bitop3:0xc8
	v_cndmask_b32_e64 v3, v3, 3, vcc
	v_cndmask_b32_e32 v2, v2, v5, vcc
	v_cmp_eq_u32_e32 vcc, 0, v4
	s_and_b64 s[8:9], s[42:43], vcc
	v_cmp_lt_f32_e32 vcc, v2, v10
	s_and_b64 vcc, s[8:9], vcc
	v_bitop3_b32 v4, v18, 32, v17 bitop3:0xc8
	v_cndmask_b32_e64 v3, v3, 4, vcc
	v_cndmask_b32_e32 v2, v2, v10, vcc
	v_cmp_eq_u32_e32 vcc, 0, v4
	s_and_b64 s[8:9], s[24:25], vcc
	v_cmp_lt_f32_e32 vcc, v2, v11
	s_and_b64 vcc, s[8:9], vcc
	v_bitop3_b32 v4, v18, 64, v17 bitop3:0xc8
	v_cndmask_b32_e64 v3, v3, 5, vcc
	v_cndmask_b32_e32 v2, v2, v11, vcc
	v_cmp_eq_u32_e32 vcc, 0, v4
	s_and_b64 s[8:9], s[80:81], vcc
	v_cmp_lt_f32_e32 vcc, v2, v12
	s_and_b64 vcc, s[8:9], vcc
	s_movk_i32 s8, 0x80
	v_bitop3_b32 v4, v18, s8, v17 bitop3:0xc8
	v_cndmask_b32_e64 v3, v3, 6, vcc
	v_cndmask_b32_e32 v2, v2, v12, vcc
	v_cmp_eq_u32_e32 vcc, 0, v4
	s_and_b64 s[6:7], s[6:7], vcc
	v_cmp_lt_f32_e32 vcc, v2, v13
	s_and_b64 vcc, s[6:7], vcc
	s_movk_i32 s6, 0x100
	v_bitop3_b32 v4, v18, s6, v17 bitop3:0xc8
	v_cndmask_b32_e64 v3, v3, 7, vcc
	v_cndmask_b32_e32 v2, v2, v13, vcc
	v_cmp_eq_u32_e32 vcc, 0, v4
	s_and_b64 s[6:7], s[26:27], vcc
	v_cmp_lt_f32_e32 vcc, v2, v6
	s_and_b64 vcc, s[6:7], vcc
	s_movk_i32 s6, 0x200
	v_bitop3_b32 v4, v18, s6, v17 bitop3:0xc8
	v_cndmask_b32_e64 v3, v3, 8, vcc
	v_cndmask_b32_e32 v2, v2, v6, vcc
	v_cmp_eq_u32_e32 vcc, 0, v4
	s_and_b64 s[0:1], s[0:1], vcc
	v_cmp_lt_f32_e32 vcc, v2, v7
	s_and_b64 vcc, s[0:1], vcc
	s_movk_i32 s0, 0x400
	v_bitop3_b32 v4, v18, s0, v17 bitop3:0xc8
	v_cndmask_b32_e64 v3, v3, 9, vcc
	v_cndmask_b32_e32 v2, v2, v7, vcc
	v_cmp_eq_u32_e32 vcc, 0, v4
	s_and_b64 s[0:1], s[98:99], vcc
	v_cmp_lt_f32_e32 vcc, v2, v8
	s_and_b64 vcc, s[0:1], vcc
	s_movk_i32 s0, 0x800
	v_bitop3_b32 v4, v18, s0, v17 bitop3:0xc8
	v_cndmask_b32_e64 v3, v3, 10, vcc
	v_cndmask_b32_e32 v2, v2, v8, vcc
	v_cmp_eq_u32_e32 vcc, 0, v4
	s_and_b64 s[0:1], s[96:97], vcc
	v_cmp_lt_f32_e32 vcc, v2, v9
	s_and_b64 vcc, s[0:1], vcc
	s_movk_i32 s0, 0x1000
	v_bitop3_b32 v4, v18, s0, v17 bitop3:0xc8
	v_cndmask_b32_e64 v3, v3, 11, vcc
	v_cndmask_b32_e32 v2, v2, v9, vcc
	v_cmp_eq_u32_e32 vcc, 0, v4
	s_and_b64 s[0:1], s[94:95], vcc
	v_cmp_lt_f32_e32 vcc, v2, v14
	s_and_b64 vcc, s[0:1], vcc
	s_movk_i32 s0, 0x2000
	v_bitop3_b32 v4, v18, s0, v17 bitop3:0xc8
	v_cndmask_b32_e64 v3, v3, 12, vcc
	v_cndmask_b32_e32 v2, v2, v14, vcc
	v_cmp_eq_u32_e32 vcc, 0, v4
	s_and_b64 s[0:1], s[90:91], vcc
	v_cmp_lt_f32_e32 vcc, v2, v15
	s_and_b64 vcc, s[0:1], vcc
	s_movk_i32 s0, 0x4000
	v_bitop3_b32 v4, v18, s0, v17 bitop3:0xc8
	v_cndmask_b32_e64 v3, v3, 13, vcc
	v_cndmask_b32_e32 v2, v2, v15, vcc
	v_cmp_eq_u32_e32 vcc, 0, v4
	s_and_b64 s[0:1], s[12:13], vcc
	v_cmp_lt_f32_e32 vcc, v2, v16
	s_and_b64 s[0:1], s[0:1], vcc
	v_cndmask_b32_e64 v2, v3, 14, s[0:1]
	v_lshlrev_b32_e64 v3, v2, 1
	v_cmp_lt_i32_e32 vcc, -1, v2
	v_readlane_b32 s98, v255, 43
	v_readlane_b32 s96, v255, 41
	v_cndmask_b32_e32 v2, 0, v3, vcc
	v_readlane_b32 s99, v255, 44
	v_readlane_b32 s97, v255, 42
	s_mov_b32 s91, 0x41000000
	v_or_b32_e32 v165, v2, v19
	s_mov_b64 s[0:1], 0
